# v114 + grid barrier release: all workgroups poll the top-level arrival counter (>= (gen+1)*nx) instead of the generation word bumped afterwards
# baseline (speedup 1.0000x reference)
.LBB0_1502:
	s_or_b64 exec, exec, s[2:3]
	v_cvt_f32_u32_e32 v4, v2
	s_waitcnt vmcnt(0)
	v_readfirstlane_b32 s2, v3
	v_sub_u32_e32 v3, 0, v2
	v_rcp_iflag_f32_e32 v4, v4
	v_add_u32_e32 v5, s2, v1
	v_mul_f32_e32 v4, 0x4f7ffffe, v4
	v_cvt_u32_f32_e32 v4, v4
	v_mul_lo_u32 v1, v3, v4
	v_mul_hi_u32 v1, v4, v1
	v_add_u32_e32 v1, v4, v1
	v_mul_hi_u32 v1, v5, v1
	v_mul_lo_u32 v3, v1, v2
	v_sub_u32_e32 v3, v5, v3
	v_add_u32_e32 v4, 1, v1
	v_cmp_ge_u32_e32 vcc, v3, v2
	s_nop 1
	v_cndmask_b32_e32 v1, v1, v4, vcc
	v_sub_u32_e32 v4, v3, v2
	v_cndmask_b32_e32 v3, v3, v4, vcc
	v_add_u32_e32 v4, 1, v1
	v_cmp_ge_u32_e32 vcc, v3, v2
	v_add_u32_e32 v3, 1, v5
	s_nop 0
	v_cndmask_b32_e32 v1, v1, v4, vcc
	v_mul_lo_u32 v4, v2, v1
	v_add_u32_e32 v2, v4, v2
	v_cmp_ne_u32_e32 vcc, v3, v2
	s_and_saveexec_b64 s[2:3], vcc
	s_xor_b64 s[2:3], exec, s[2:3]
	s_cbranch_execz .LBB0_1516
	v_add_u32_e32 v4, 1, v1
	v_mul_lo_u32 v4, v4, v0
	v_readlane_b32 s4, v251, 24
	v_readlane_b32 s5, v251, 25
	s_waitcnt lgkmcnt(0)
	s_nop 3
	global_load_dword v0, v31, s[4:5] sc1
	s_waitcnt vmcnt(0)
	v_cmp_lt_u32_e32 vcc, v0, v4
	s_and_saveexec_b64 s[4:5], vcc
	s_cbranch_execz .LBB0_1515
	s_mov_b32 s16, 1
	s_mov_b64 s[6:7], 0
	s_branch .LBB0_1506

.LBB0_1510:
	v_readlane_b32 s10, v251, 24
	v_readlane_b32 s11, v251, 25
	s_add_i32 s16, s16, 1
	s_mov_b64 s[12:13], -1
	s_nop 2
	global_load_dword v0, v31, s[10:11] sc1
	s_waitcnt vmcnt(0)
	v_cmp_ge_u32_e32 vcc, v0, v4
	s_orn2_b64 s[10:11], vcc, exec
	s_branch .LBB0_1505

.LBB0_1519:
	s_or_b64 exec, exec, s[4:5]
	s_waitcnt vmcnt(0)
	v_readfirstlane_b32 s2, v2
	v_cvt_f32_u32_e32 v2, v0
	v_sub_u32_e32 v3, 0, v0
	v_add_u32_e32 v1, s2, v1
	v_readlane_b32 s2, v251, 26
	v_rcp_iflag_f32_e32 v2, v2
	v_readlane_b32 s3, v251, 27
	s_mov_b64 s[4:5], -1
	v_mul_f32_e32 v2, 0x4f7ffffe, v2
	v_cvt_u32_f32_e32 v2, v2
	v_mul_lo_u32 v3, v3, v2
	v_mul_hi_u32 v3, v2, v3
	v_add_u32_e32 v2, v2, v3
	v_mul_hi_u32 v2, v1, v2
	v_mul_lo_u32 v3, v2, v0
	v_sub_u32_e32 v3, v1, v3
	v_cmp_ge_u32_e32 vcc, v3, v0
	v_add_u32_e32 v4, 1, v2
	v_add_u32_e32 v1, 1, v1
	v_cndmask_b32_e32 v2, v2, v4, vcc
	v_sub_u32_e32 v4, v3, v0
	v_cndmask_b32_e32 v3, v3, v4, vcc
	v_cmp_ge_u32_e32 vcc, v3, v0
	v_add_u32_e32 v3, 1, v2
	s_nop 0
	v_cndmask_b32_e32 v2, v2, v3, vcc
	v_mul_lo_u32 v3, v0, v2
	v_add_u32_e32 v0, v3, v0
	v_cmp_ne_u32_e32 vcc, v1, v0
	v_mov_b32_e32 v4, v0
	v_mov_b64_e32 v[0:1], s[2:3]
	s_and_saveexec_b64 s[2:3], vcc
	s_cbranch_execz .LBB0_1531
	v_readlane_b32 s4, v251, 24
	v_readlane_b32 s5, v251, 25
	s_mov_b64 s[6:7], 0
	s_nop 3
	global_load_dword v0, v31, s[4:5] sc1
	s_waitcnt vmcnt(0)
	v_cmp_lt_u32_e32 vcc, v0, v4
	s_and_saveexec_b64 s[4:5], vcc
	s_cbranch_execz .LBB0_1530
	s_mov_b32 s16, 1
	s_branch .LBB0_1523
